# phase 2: every other group of eight workgroups produces its filter share before its three GEMM tiles, the others after (tile epilogues of the two halves interleave)
# speedup vs baseline: 1.0240x; 1.0035x over previous
.LBB0_207:
.LBB0_208:
	s_cmp_lt_i32 s68, 3
	s_cselect_b64 s[8:9], -1, 0
	s_and_b64 s[8:9], s[8:9], s[6:7]
	s_andn2_b64 vcc, exec, s[8:9]
	v_writelane_b32 v240, s0, 22
	s_nop 1
	v_writelane_b32 v240, s1, 23
	s_cbranch_vccnz .LBB0_225
	s_cmpk_lg_u32 s70, 0x100
	s_cbranch_scc1 .Lp2_tiles
	s_bitcmp1_b32 s2, 3
	s_cbranch_scc1 .Lpf_begin
.Lp2_tiles:
	s_cmpk_gt_i32 s2, 0x2ff
	v_readfirstlane_b32 s7, v1
	s_cbranch_scc1 .LBB0_225
	v_lshrrev_b32_e32 v4, 1, v1
	v_and_b32_e32 v13, 24, v4
	v_lshrrev_b32_e32 v4, 5, v1
	v_and_b32_e32 v4, 4, v4
	v_bfe_u32 v5, v1, 2, 2
	s_add_u32 s33, s66, 0xa00000
	v_lshlrev_b32_e32 v2, 4, v1
	v_and_b32_e32 v3, 32, v1
	v_bfe_u32 v12, v1, 2, 4
	v_or3_b32 v4, v4, v5, v13
	v_lshrrev_b32_e32 v5, 3, v1
	s_movk_i32 s6, 0x70
	s_addc_u32 s46, s67, 0
	v_bitop3_b32 v10, v2, v3, 48 bitop3:0x6c
	v_and_b32_e32 v11, 64, v1
	v_and_or_b32 v6, v5, s6, v12
	s_movk_i32 s6, 0x60
	v_add_u32_e32 v14, 0x2000, v2
	s_add_u32 s47, s66, 0x1c00000
	v_or_b32_e32 v3, v10, v11
	v_and_or_b32 v5, v5, s6, v4
	v_lshrrev_b32_e32 v2, 7, v14
	s_movk_i32 s6, 0xf0
	s_addc_u32 s58, s67, 0
	v_lshl_or_b32 v132, v5, 11, v3
	v_and_or_b32 v5, v2, s6, v12
	s_movk_i32 s6, 0xe0
	s_ashr_i32 s60, s2, 31
	v_and_or_b32 v2, v2, s6, v4
	s_lshr_b32 s6, s60, 29
	s_add_i32 s6, s2, s6
	s_lshr_b32 s14, s7, 6
	s_ashr_i32 s10, s6, 3
	s_and_b32 s6, s6, -8
	s_lshr_b32 s16, s7, 8
	s_lshl_b32 s59, s14, 10
	s_sub_i32 s6, s2, s6
	s_cmp_lt_i32 s6, 0
	s_movk_i32 s61, 0x61
	s_cselect_b32 s11, s61, 0x60
	s_mul_i32 s6, s6, s11
	s_add_i32 s6, s6, s10
	s_ashr_i32 s10, s6, 31
	s_lshr_b32 s10, s10, 24
	s_add_i32 s10, s6, s10
	s_ashr_i32 s11, s10, 8
	s_and_b32 s10, s10, 0xffffff00
	s_sub_i32 s10, s6, s10
	s_sext_i32_i16 s6, s10
	s_bfe_u32 s6, s6, 0x2001d
	s_add_i32 s12, s10, s6
	s_sext_i32_i16 s6, s12
	s_and_b32 s12, s12, 0xfffc
	s_sub_i32 s10, s10, s12
	s_lshl_b32 s11, s11, 2
	s_sext_i32_i16 s10, s10
	s_add_i32 s28, s11, s10
	s_ashr_i32 s29, s28, 31
	s_lshr_b32 s6, s6, 2
	s_lshl_b64 s[10:11], s[28:29], 19
	s_add_u32 s42, s33, s10
	s_addc_u32 s43, s46, s11
	s_bfe_i64 s[10:11], s[6:7], 0x100000
	s_lshl_b64 s[10:11], s[10:11], 19
	s_add_u32 s48, s47, s10
	s_addc_u32 s49, s58, s11
	s_add_i32 s29, s59, 0
	s_add_i32 m0, s29, 0x10000
	v_lshl_or_b32 v136, v2, 11, v3
	global_load_lds_dwordx4 v132, s[48:49]
	s_add_i32 m0, s29, 0x12000
	s_add_u32 s10, s48, 0x40000
	global_load_lds_dwordx4 v136, s[48:49]
	s_addc_u32 s11, s49, 0
	s_add_i32 m0, s29, 0x14000
	s_add_i32 s62, s29, 0x2000
	global_load_lds_dwordx4 v132, s[10:11]
	s_add_i32 m0, s29, 0x16000
	v_lshl_or_b32 v130, v6, 11, v3
	global_load_lds_dwordx4 v136, s[10:11]
	s_mov_b32 m0, s29
	s_add_u32 s10, s42, 0x40000
	v_lshl_or_b32 v134, v5, 11, v3
	global_load_lds_dwordx4 v130, s[42:43]
	s_mov_b32 m0, s62
	s_addc_u32 s11, s43, 0
	s_add_i32 s63, s29, 0x4000
	global_load_lds_dwordx4 v134, s[42:43]
	s_mov_b32 m0, s63
	s_add_i32 s74, s29, 0x6000
	global_load_lds_dwordx4 v130, s[10:11]
	s_mov_b32 m0, s74
	v_mov_b32_e32 v133, 0
	global_load_lds_dwordx4 v134, s[10:11]
	v_mov_b32_e32 v137, v133
	v_mov_b32_e32 v131, v133
	v_mov_b32_e32 v135, v133
	s_cmp_eq_u32 s16, 1
	s_mov_b32 s75, 0
	v_lshl_add_u64 v[8:9], s[48:49], 0, v[132:133]
	v_lshl_add_u64 v[6:7], s[48:49], 0, v[136:137]
	v_lshl_add_u64 v[2:3], s[42:43], 0, v[130:131]
	s_cselect_b64 s[10:11], -1, 0
	s_cmp_lg_u32 s16, 1
	v_lshl_add_u64 v[4:5], s[42:43], 0, v[134:135]
	s_cbranch_scc1 .LBB0_212
	s_barrier

.LBB0_224:
	s_waitcnt vmcnt(0)
	v_readlane_b32 s0, v240, 22
	v_readlane_b32 s1, v240, 23
	s_barrier
	s_cmpk_lg_u32 s70, 0x100
	s_cbranch_scc1 .Lpf_begin
	s_bitcmp1_b32 s2, 3
	s_cbranch_scc1 .Lpf_done
.Lpf_begin:
	v_and_b32_e32 v2, 63, v1
	v_and_b32_e32 v3, 31, v2
	v_lshrrev_b32_e32 v4, 5, v2
	v_lshrrev_b32_e32 v6, 6, v1
	v_mov_b32_e32 v82, 0
	s_mov_b32 s61, 0x447fc000
	v_readfirstlane_b32 s92, v6
	v_cmp_eq_u32_e64 s[14:15], 1, v4
	v_mov_b32_e32 v8, 0x3d4ccccd
	v_mov_b32_e32 v9, 0x3d4ccccd
	s_mov_b32 s93, s2
.Lpf_item:
	s_cmpk_gt_u32 s93, 0xff
	s_cbranch_scc1 .Lpf_end
	s_lshr_b32 s94, s93, 5
	s_lshl_b32 s94, s94, 3
	s_add_i32 s94, s94, s92
	s_and_b32 s95, s93, 31
	s_lshl_b32 s96, s94, 4
	v_bfe_u32 v7, v3, 2, 1
	v_lshrrev_b32_e32 v6, 3, v3
	v_and_b32_e32 v10, 3, v3
	v_lshlrev_b32_e32 v7, 10, v7
	v_lshl_add_u32 v7, v6, 2, v7
	v_add_u32_e32 v7, v7, v10
	v_add_u32_e32 v7, s96, v7
	v_lshlrev_b32_e32 v7, 2, v7
	v_lshl_add_u32 v80, v4, 16, v7
	global_load_dword v84, v80, s[86:87]
	s_add_u32 s90, s86, 0x2000
	s_addc_u32 s91, s87, 0
	global_load_dword v85, v80, s[90:91]
	s_add_u32 s90, s86, 0x4000
	s_addc_u32 s91, s87, 0
	global_load_dword v86, v80, s[90:91]
	s_add_u32 s90, s86, 0x6000
	s_addc_u32 s91, s87, 0
	global_load_dword v87, v80, s[90:91]
	s_add_u32 s90, s86, 0x8000
	s_addc_u32 s91, s87, 0
	global_load_dword v88, v80, s[90:91]
	s_add_u32 s90, s86, 0xa000
	s_addc_u32 s91, s87, 0
	global_load_dword v89, v80, s[90:91]
	s_add_u32 s90, s86, 0xc000
	s_addc_u32 s91, s87, 0
	global_load_dword v90, v80, s[90:91]
	s_add_u32 s90, s86, 0xe000
	s_addc_u32 s91, s87, 0
	global_load_dword v91, v80, s[90:91]
	s_add_u32 s90, s86, 0x20000
	s_addc_u32 s91, s87, 0
	global_load_dword v92, v80, s[90:91]
	s_add_u32 s90, s86, 0x22000
	s_addc_u32 s91, s87, 0
	global_load_dword v93, v80, s[90:91]
	s_add_u32 s90, s86, 0x24000
	s_addc_u32 s91, s87, 0
	global_load_dword v94, v80, s[90:91]
	s_add_u32 s90, s86, 0x26000
	s_addc_u32 s91, s87, 0
	global_load_dword v95, v80, s[90:91]
	s_add_u32 s90, s86, 0x28000
	s_addc_u32 s91, s87, 0
	global_load_dword v96, v80, s[90:91]
	s_add_u32 s90, s86, 0x2a000
	s_addc_u32 s91, s87, 0
	global_load_dword v97, v80, s[90:91]
	s_add_u32 s90, s86, 0x2c000
	s_addc_u32 s91, s87, 0
	global_load_dword v98, v80, s[90:91]
	s_add_u32 s90, s86, 0x2e000
	s_addc_u32 s91, s87, 0
	global_load_dword v99, v80, s[90:91]
	s_add_u32 s90, s86, 0x40000
	s_addc_u32 s91, s87, 0
	global_load_dword v100, v80, s[90:91]
	s_add_u32 s90, s86, 0x42000
	s_addc_u32 s91, s87, 0
	global_load_dword v101, v80, s[90:91]
	s_add_u32 s90, s86, 0x44000
	s_addc_u32 s91, s87, 0
	global_load_dword v102, v80, s[90:91]
	s_add_u32 s90, s86, 0x46000
	s_addc_u32 s91, s87, 0
	global_load_dword v103, v80, s[90:91]
	s_add_u32 s90, s86, 0x48000
	s_addc_u32 s91, s87, 0
	global_load_dword v104, v80, s[90:91]
	s_add_u32 s90, s86, 0x4a000
	s_addc_u32 s91, s87, 0
	global_load_dword v105, v80, s[90:91]
	s_add_u32 s90, s86, 0x4c000
	s_addc_u32 s91, s87, 0
	global_load_dword v106, v80, s[90:91]
	s_add_u32 s90, s86, 0x4e000
	s_addc_u32 s91, s87, 0
	global_load_dword v107, v80, s[90:91]
	s_add_u32 s90, s86, 0x60000
	s_addc_u32 s91, s87, 0
	global_load_dword v108, v80, s[90:91]
	s_add_u32 s90, s86, 0x62000
	s_addc_u32 s91, s87, 0
	global_load_dword v109, v80, s[90:91]
	s_add_u32 s90, s86, 0x64000
	s_addc_u32 s91, s87, 0
	global_load_dword v110, v80, s[90:91]
	s_add_u32 s90, s86, 0x66000
	s_addc_u32 s91, s87, 0
	global_load_dword v111, v80, s[90:91]
	s_add_u32 s90, s86, 0x68000
	s_addc_u32 s91, s87, 0
	global_load_dword v76, v80, s[90:91]
	s_add_u32 s90, s86, 0x6a000
	s_addc_u32 s91, s87, 0
	global_load_dword v77, v80, s[90:91]
	s_add_u32 s90, s86, 0x6c000
	s_addc_u32 s91, s87, 0
	global_load_dword v78, v80, s[90:91]
	s_add_u32 s90, s86, 0x6e000
	s_addc_u32 s91, s87, 0
	global_load_dword v79, v80, s[90:91]
	s_lshr_b32 s72, s92, 1
	s_and_b32 s73, s92, 1
	s_lshl_b32 s55, s95, 14
	s_lshl_b32 s76, s72, 12
	s_add_i32 s55, s55, s76
	s_lshl_b32 s76, s73, 19
	s_add_i32 s55, s55, s76
	s_add_u32 s78, s66, 0x1a80000
	s_addc_u32 s79, s67, 0
	s_add_u32 s78, s78, s55
	s_addc_u32 s79, s79, 0
	s_lshl_b32 s76, s72, 13
	s_lshl_b32 s77, s73, 12
	s_add_i32 s76, s76, s77
	v_lshrrev_b32_e32 v6, 3, v2
	v_and_b32_e32 v7, 7, v2
	v_and_b32_e32 v10, 7, v6
	v_xor_b32_e32 v7, v7, v10
	v_lshlrev_b32_e32 v7, 4, v7
	v_lshl_add_u32 v81, v6, 7, v7
	s_add_i32 m0, s76, 0x0
	s_nop 0
	global_load_lds_dwordx4 v81, s[78:79]
	s_add_i32 m0, s76, 0x400
	s_add_u32 s78, s78, 0x400
	s_addc_u32 s79, s79, 0
	global_load_lds_dwordx4 v81, s[78:79]
	s_add_i32 m0, s76, 0x800
	s_add_u32 s78, s78, 0x400
	s_addc_u32 s79, s79, 0
	global_load_lds_dwordx4 v81, s[78:79]
	s_add_i32 m0, s76, 0xc00
	s_add_u32 s78, s78, 0x400
	s_addc_u32 s79, s79, 0
	global_load_lds_dwordx4 v81, s[78:79]
	v_and_b32_e32 v6, 7, v3
	v_add_u32_e32 v7, 0, v4
	v_xor_b32_e32 v7, v7, v6
	v_lshlrev_b32_e32 v7, 4, v7
	v_lshl_add_u32 v48, v3, 7, v7
	v_add_u32_e32 v7, 2, v4
	v_xor_b32_e32 v7, v7, v6
	v_lshlrev_b32_e32 v7, 4, v7
	v_lshl_add_u32 v49, v3, 7, v7
	v_add_u32_e32 v7, 4, v4
	v_xor_b32_e32 v7, v7, v6
	v_lshlrev_b32_e32 v7, 4, v7
	v_lshl_add_u32 v50, v3, 7, v7
	v_add_u32_e32 v7, 6, v4
	v_xor_b32_e32 v7, v7, v6
	v_lshlrev_b32_e32 v7, 4, v7
	v_lshl_add_u32 v51, v3, 7, v7
	s_lshl_b32 s55, s96, 14
	s_add_u32 s84, s66, 0x9c00000
	s_addc_u32 s85, s67, 0
	s_add_u32 s84, s84, s55
	s_addc_u32 s85, s85, 0
	v_and_b32_e32 v6, 15, v2
	v_add_u32_e32 v6, s96, v6
	v_cvt_f32_u32_e32 v6, v6
	v_div_scale_f32 v7, s[16:17], s61, s61, v6
	v_rcp_f32_e32 v12, v7
	v_div_scale_f32 v13, vcc, v6, s61, v6
	v_fma_f32 v10, -v7, v12, 1.0
	v_fmac_f32_e32 v12, v10, v12
	v_mul_f32_e32 v10, v13, v12
	v_fma_f32 v11, -v7, v10, v13
	v_fmac_f32_e32 v10, v11, v12
	v_fma_f32 v7, -v7, v10, v13
	s_nop 1
	v_div_fmas_f32 v7, v7, v12, v10
	v_div_fixup_f32 v6, v7, s61, v6
	v_mov_b32_e32 v7, 0xc0447cbd
	v_fmamk_f32 v6, v6, 0xc1447cbd, v7
	v_and_b32_e32 v6, 0x7fffffff, v6
	s_nop 0
	v_readlane_b32 s6, v6, 0
	v_readlane_b32 s7, v6, 1
	v_readlane_b32 s10, v6, 2
	v_readlane_b32 s11, v6, 3
	v_readlane_b32 s24, v6, 4
	v_readlane_b32 s62, v6, 5
	v_readlane_b32 s32, v6, 6
	v_readlane_b32 s75, v6, 7
	v_readlane_b32 s41, v6, 8
	v_readlane_b32 s44, v6, 9
	v_readlane_b32 s45, v6, 10
	v_readlane_b32 s47, v6, 11
	v_readlane_b32 s48, v6, 12
	v_readlane_b32 s49, v6, 13
	v_readlane_b32 s52, v6, 14
	v_readlane_b32 s53, v6, 15
	s_waitcnt vmcnt(0)
	v_cvt_pk_bf16_f32 v6, v84, v85
	v_lshlrev_b32_e32 v12, 16, v6
	v_and_b32_e32 v13, 0xffff0000, v6
	v_sub_f32_e32 v84, v84, v12
	v_sub_f32_e32 v85, v85, v13
	v_cvt_pk_bf16_f32 v70, v84, v85
	v_cvt_pk_bf16_f32 v7, v86, v87
	v_lshlrev_b32_e32 v12, 16, v7
	v_and_b32_e32 v13, 0xffff0000, v7
	v_sub_f32_e32 v86, v86, v12
	v_sub_f32_e32 v87, v87, v13
	v_cvt_pk_bf16_f32 v71, v86, v87
	v_cvt_pk_bf16_f32 v10, v88, v89
	v_lshlrev_b32_e32 v12, 16, v10
	v_and_b32_e32 v13, 0xffff0000, v10
	v_sub_f32_e32 v88, v88, v12
	v_sub_f32_e32 v89, v89, v13
	v_cvt_pk_bf16_f32 v72, v88, v89
	v_cvt_pk_bf16_f32 v11, v90, v91
	v_lshlrev_b32_e32 v12, 16, v11
	v_and_b32_e32 v13, 0xffff0000, v11
	v_sub_f32_e32 v90, v90, v12
	v_sub_f32_e32 v91, v91, v13
	v_cvt_pk_bf16_f32 v73, v90, v91
	v_mov_b32_e32 v84, v6
	v_mov_b32_e32 v88, v70
	v_mov_b32_e32 v85, v7
	v_mov_b32_e32 v89, v71
	v_mov_b32_e32 v86, v10
	v_mov_b32_e32 v90, v72
	v_mov_b32_e32 v87, v11
	v_mov_b32_e32 v91, v73
	v_cvt_pk_bf16_f32 v6, v92, v93
	v_lshlrev_b32_e32 v12, 16, v6
	v_and_b32_e32 v13, 0xffff0000, v6
	v_sub_f32_e32 v92, v92, v12
	v_sub_f32_e32 v93, v93, v13
	v_cvt_pk_bf16_f32 v70, v92, v93
	v_cvt_pk_bf16_f32 v7, v94, v95
	v_lshlrev_b32_e32 v12, 16, v7
	v_and_b32_e32 v13, 0xffff0000, v7
	v_sub_f32_e32 v94, v94, v12
	v_sub_f32_e32 v95, v95, v13
	v_cvt_pk_bf16_f32 v71, v94, v95
	v_cvt_pk_bf16_f32 v10, v96, v97
	v_lshlrev_b32_e32 v12, 16, v10
	v_and_b32_e32 v13, 0xffff0000, v10
	v_sub_f32_e32 v96, v96, v12
	v_sub_f32_e32 v97, v97, v13
	v_cvt_pk_bf16_f32 v72, v96, v97
	v_cvt_pk_bf16_f32 v11, v98, v99
	v_lshlrev_b32_e32 v12, 16, v11
	v_and_b32_e32 v13, 0xffff0000, v11
	v_sub_f32_e32 v98, v98, v12
	v_sub_f32_e32 v99, v99, v13
	v_cvt_pk_bf16_f32 v73, v98, v99
	v_mov_b32_e32 v92, v6
	v_mov_b32_e32 v96, v70
	v_mov_b32_e32 v93, v7
	v_mov_b32_e32 v97, v71
	v_mov_b32_e32 v94, v10
	v_mov_b32_e32 v98, v72
	v_mov_b32_e32 v95, v11
	v_mov_b32_e32 v99, v73
	v_cvt_pk_bf16_f32 v6, v100, v101
	v_lshlrev_b32_e32 v12, 16, v6
	v_and_b32_e32 v13, 0xffff0000, v6
	v_sub_f32_e32 v100, v100, v12
	v_sub_f32_e32 v101, v101, v13
	v_cvt_pk_bf16_f32 v70, v100, v101
	v_cvt_pk_bf16_f32 v7, v102, v103
	v_lshlrev_b32_e32 v12, 16, v7
	v_and_b32_e32 v13, 0xffff0000, v7
	v_sub_f32_e32 v102, v102, v12
	v_sub_f32_e32 v103, v103, v13
	v_cvt_pk_bf16_f32 v71, v102, v103
	v_cvt_pk_bf16_f32 v10, v104, v105
	v_lshlrev_b32_e32 v12, 16, v10
	v_and_b32_e32 v13, 0xffff0000, v10
	v_sub_f32_e32 v104, v104, v12
	v_sub_f32_e32 v105, v105, v13
	v_cvt_pk_bf16_f32 v72, v104, v105
	v_cvt_pk_bf16_f32 v11, v106, v107
	v_lshlrev_b32_e32 v12, 16, v11
	v_and_b32_e32 v13, 0xffff0000, v11
	v_sub_f32_e32 v106, v106, v12
	v_sub_f32_e32 v107, v107, v13
	v_cvt_pk_bf16_f32 v73, v106, v107
	v_mov_b32_e32 v100, v6
	v_mov_b32_e32 v104, v70
	v_mov_b32_e32 v101, v7
	v_mov_b32_e32 v105, v71
	v_mov_b32_e32 v102, v10
	v_mov_b32_e32 v106, v72
	v_mov_b32_e32 v103, v11
	v_mov_b32_e32 v107, v73
	v_cvt_pk_bf16_f32 v6, v108, v109
	v_lshlrev_b32_e32 v12, 16, v6
	v_and_b32_e32 v13, 0xffff0000, v6
	v_sub_f32_e32 v108, v108, v12
	v_sub_f32_e32 v109, v109, v13
	v_cvt_pk_bf16_f32 v70, v108, v109
	v_cvt_pk_bf16_f32 v7, v110, v111
	v_lshlrev_b32_e32 v12, 16, v7
	v_and_b32_e32 v13, 0xffff0000, v7
	v_sub_f32_e32 v110, v110, v12
	v_sub_f32_e32 v111, v111, v13
	v_cvt_pk_bf16_f32 v71, v110, v111
	v_cvt_pk_bf16_f32 v10, v76, v77
	v_lshlrev_b32_e32 v12, 16, v10
	v_and_b32_e32 v13, 0xffff0000, v10
	v_sub_f32_e32 v76, v76, v12
	v_sub_f32_e32 v77, v77, v13
	v_cvt_pk_bf16_f32 v72, v76, v77
	v_cvt_pk_bf16_f32 v11, v78, v79
	v_lshlrev_b32_e32 v12, 16, v11
	v_and_b32_e32 v13, 0xffff0000, v11
	v_sub_f32_e32 v78, v78, v12
	v_sub_f32_e32 v79, v79, v13
	v_cvt_pk_bf16_f32 v73, v78, v79
	v_mov_b32_e32 v108, v6
	v_mov_b32_e32 v76, v70
	v_mov_b32_e32 v109, v7
	v_mov_b32_e32 v77, v71
	v_mov_b32_e32 v110, v10
	v_mov_b32_e32 v78, v72
	v_mov_b32_e32 v111, v11
	v_mov_b32_e32 v79, v73
	s_lshl_b32 s55, s95, 7
	s_barrier
	ds_read_b128 v[112:115], v48 offset:0
	ds_read_b128 v[116:119], v49 offset:0
	ds_read_b128 v[120:123], v50 offset:0
	ds_read_b128 v[124:127], v51 offset:0
	ds_read_b128 v[128:131], v48 offset:4096
	ds_read_b128 v[132:135], v49 offset:4096
	ds_read_b128 v[136:139], v50 offset:4096
	ds_read_b128 v[140:143], v51 offset:4096
	s_waitcnt lgkmcnt(0)
	s_nop 1
	ds_read_b128 v[144:147], v48 offset:8192
	ds_read_b128 v[148:151], v49 offset:8192
	ds_read_b128 v[152:155], v50 offset:8192
	ds_read_b128 v[156:159], v51 offset:8192
	ds_read_b128 v[160:163], v48 offset:12288
	ds_read_b128 v[164:167], v49 offset:12288
	ds_read_b128 v[168:171], v50 offset:12288
	ds_read_b128 v[172:175], v51 offset:12288
	v_mfma_f32_32x32x16_bf16 v[14:29], v[84:87], v[112:115], 0
	v_mfma_f32_32x32x16_bf16 v[14:29], v[84:87], v[128:131], v[14:29]
	v_mfma_f32_32x32x16_bf16 v[14:29], v[88:91], v[112:115], v[14:29]
	v_mfma_f32_32x32x16_bf16 v[14:29], v[92:95], v[116:119], v[14:29]
	v_mfma_f32_32x32x16_bf16 v[14:29], v[92:95], v[132:135], v[14:29]
	v_mfma_f32_32x32x16_bf16 v[14:29], v[96:99], v[116:119], v[14:29]
	v_mfma_f32_32x32x16_bf16 v[14:29], v[100:103], v[120:123], v[14:29]
	v_mfma_f32_32x32x16_bf16 v[14:29], v[100:103], v[136:139], v[14:29]
	v_mfma_f32_32x32x16_bf16 v[14:29], v[104:107], v[120:123], v[14:29]
	v_mfma_f32_32x32x16_bf16 v[14:29], v[108:111], v[124:127], v[14:29]
	v_mfma_f32_32x32x16_bf16 v[14:29], v[108:111], v[140:143], v[14:29]
	v_mfma_f32_32x32x16_bf16 v[14:29], v[76:79], v[124:127], v[14:29]
	s_waitcnt lgkmcnt(0)
	ds_read_b128 v[112:115], v48 offset:16384
	ds_read_b128 v[116:119], v49 offset:16384
	ds_read_b128 v[120:123], v50 offset:16384
	ds_read_b128 v[124:127], v51 offset:16384
	ds_read_b128 v[128:131], v48 offset:20480
	ds_read_b128 v[132:135], v49 offset:20480
	ds_read_b128 v[136:139], v50 offset:20480
	ds_read_b128 v[140:143], v51 offset:20480
	v_mfma_f32_32x32x16_bf16 v[32:47], v[84:87], v[144:147], 0
	v_add_u32_e32 v70, s55, v3
	v_cvt_f32_i32_e32 v71, v70
	v_mul_f32_e32 v71, 0xb9b8b5c6, v71
	v_sub_u32_e32 v72, 0x1000, v70
	v_add_u32_e32 v73, 0x1000, v70
	v_cmp_eq_u32_e32 vcc, 0, v70
	s_and_b64 s[16:17], vcc, s[14:15]
	s_andn2_b64 s[18:19], vcc, s[14:15]
	v_cndmask_b32_e64 v73, v73, 0, vcc
	v_cndmask_b32_e64 v72, v72, v73, s[14:15]
	v_lshlrev_b32_e32 v72, 1, v72
	s_mov_b64 s[90:91], s[84:85]
	s_add_i32 s55, s55, 32
	s_cmp_lg_u32 s95, 0
	s_cbranch_scc1 .Lpf_noskip
	s_lshl_b32 s72, s96, 2
	s_add_u32 s72, s88, s72
	s_addc_u32 s73, s89, 0
	global_load_dwordx4 v[176:179], v82, s[72:73]
	global_load_dwordx4 v[180:183], v82, s[72:73] offset:16
	global_load_dwordx4 v[184:187], v82, s[72:73] offset:32
	global_load_dwordx4 v[188:191], v82, s[72:73] offset:48
	s_waitcnt vmcnt(0)
.Lpf_noskip:
	s_nop 7
	v_mfma_f32_32x32x16_bf16 v[32:47], v[84:87], v[160:163], v[32:47]
	v_mul_f32_e32 v10, s6, v71
	v_mul_f32_e32 v11, s7, v71
	v_exp_f32_e32 v10, v10
	v_exp_f32_e32 v11, v11
	s_nop 0
	v_pk_add_f32 v[10:11], v[10:11], v[8:9]
	v_pk_mul_f32 v[10:11], v[10:11], v[14:15]
	v_add_f32_e32 v6, v176, v10
	v_cndmask_b32_e64 v10, v10, v6, s[18:19]
	v_cndmask_b32_e64 v10, v10, 0, s[16:17]
	v_add_f32_e32 v6, v177, v11
	v_cndmask_b32_e64 v11, v11, v6, s[18:19]
	v_cndmask_b32_e64 v11, v11, 0, s[16:17]
	v_cvt_pk_bf16_f32 v10, v10, v11
	global_store_short v72, v10, s[90:91]
	v_mfma_f32_32x32x16_bf16 v[32:47], v[88:91], v[144:147], v[32:47]
	s_add_u32 s90, s90, 0x4000
	s_addc_u32 s91, s91, 0
	global_store_short_d16_hi v72, v10, s[90:91]
	s_add_u32 s90, s90, 0x4000
	s_addc_u32 s91, s91, 0
	v_mul_f32_e32 v12, s10, v71
	v_mul_f32_e32 v13, s11, v71
	v_exp_f32_e32 v12, v12
	v_exp_f32_e32 v13, v13
	s_nop 0
	v_pk_add_f32 v[12:13], v[12:13], v[8:9]
	v_pk_mul_f32 v[12:13], v[12:13], v[16:17]
	v_add_f32_e32 v6, v178, v12
	v_cndmask_b32_e64 v12, v12, v6, s[18:19]
	v_cndmask_b32_e64 v12, v12, 0, s[16:17]
	v_mfma_f32_32x32x16_bf16 v[32:47], v[92:95], v[148:151], v[32:47]
	v_add_f32_e32 v6, v179, v13
	v_cndmask_b32_e64 v13, v13, v6, s[18:19]
	v_cndmask_b32_e64 v13, v13, 0, s[16:17]
	v_cvt_pk_bf16_f32 v12, v12, v13
	global_store_short v72, v12, s[90:91]
	s_add_u32 s90, s90, 0x4000
	s_addc_u32 s91, s91, 0
	global_store_short_d16_hi v72, v12, s[90:91]
	s_add_u32 s90, s90, 0x4000
	s_addc_u32 s91, s91, 0
	v_mul_f32_e32 v10, s24, v71
	v_mul_f32_e32 v11, s62, v71
	v_exp_f32_e32 v10, v10
	v_exp_f32_e32 v11, v11
	s_nop 0
	v_mfma_f32_32x32x16_bf16 v[32:47], v[92:95], v[164:167], v[32:47]
	v_pk_add_f32 v[10:11], v[10:11], v[8:9]
	v_pk_mul_f32 v[10:11], v[10:11], v[18:19]
	v_add_f32_e32 v6, v180, v10
	v_cndmask_b32_e64 v10, v10, v6, s[18:19]
	v_cndmask_b32_e64 v10, v10, 0, s[16:17]
	v_add_f32_e32 v6, v181, v11
	v_cndmask_b32_e64 v11, v11, v6, s[18:19]
	v_cndmask_b32_e64 v11, v11, 0, s[16:17]
	v_cvt_pk_bf16_f32 v10, v10, v11
	global_store_short v72, v10, s[90:91]
	s_add_u32 s90, s90, 0x4000
	s_addc_u32 s91, s91, 0
	global_store_short_d16_hi v72, v10, s[90:91]
	s_add_u32 s90, s90, 0x4000
	s_addc_u32 s91, s91, 0
	v_mfma_f32_32x32x16_bf16 v[32:47], v[96:99], v[148:151], v[32:47]
	v_mul_f32_e32 v12, s32, v71
	v_mul_f32_e32 v13, s75, v71
	v_exp_f32_e32 v12, v12
	v_exp_f32_e32 v13, v13
	s_nop 0
	v_pk_add_f32 v[12:13], v[12:13], v[8:9]
	v_pk_mul_f32 v[12:13], v[12:13], v[20:21]
	v_add_f32_e32 v6, v182, v12
	v_cndmask_b32_e64 v12, v12, v6, s[18:19]
	v_cndmask_b32_e64 v12, v12, 0, s[16:17]
	v_add_f32_e32 v6, v183, v13
	v_cndmask_b32_e64 v13, v13, v6, s[18:19]
	v_cndmask_b32_e64 v13, v13, 0, s[16:17]
	v_cvt_pk_bf16_f32 v12, v12, v13
	global_store_short v72, v12, s[90:91]
	v_mfma_f32_32x32x16_bf16 v[32:47], v[100:103], v[152:155], v[32:47]
	s_add_u32 s90, s90, 0x4000
	s_addc_u32 s91, s91, 0
	global_store_short_d16_hi v72, v12, s[90:91]
	s_add_u32 s90, s90, 0x4000
	s_addc_u32 s91, s91, 0
	v_mul_f32_e32 v10, s41, v71
	v_mul_f32_e32 v11, s44, v71
	v_exp_f32_e32 v10, v10
	v_exp_f32_e32 v11, v11
	s_nop 0
	v_pk_add_f32 v[10:11], v[10:11], v[8:9]
	v_pk_mul_f32 v[10:11], v[10:11], v[22:23]
	v_add_f32_e32 v6, v184, v10
	v_cndmask_b32_e64 v10, v10, v6, s[18:19]
	v_cndmask_b32_e64 v10, v10, 0, s[16:17]
	v_mfma_f32_32x32x16_bf16 v[32:47], v[100:103], v[168:171], v[32:47]
	v_add_f32_e32 v6, v185, v11
	v_cndmask_b32_e64 v11, v11, v6, s[18:19]
	v_cndmask_b32_e64 v11, v11, 0, s[16:17]
	v_cvt_pk_bf16_f32 v10, v10, v11
	global_store_short v72, v10, s[90:91]
	s_add_u32 s90, s90, 0x4000
	s_addc_u32 s91, s91, 0
	global_store_short_d16_hi v72, v10, s[90:91]
	s_add_u32 s90, s90, 0x4000
	s_addc_u32 s91, s91, 0
	v_mul_f32_e32 v12, s45, v71
	v_mul_f32_e32 v13, s47, v71
	v_exp_f32_e32 v12, v12
	v_exp_f32_e32 v13, v13
	s_nop 0
	v_mfma_f32_32x32x16_bf16 v[32:47], v[104:107], v[152:155], v[32:47]
	v_pk_add_f32 v[12:13], v[12:13], v[8:9]
	v_pk_mul_f32 v[12:13], v[12:13], v[24:25]
	v_add_f32_e32 v6, v186, v12
	v_cndmask_b32_e64 v12, v12, v6, s[18:19]
	v_cndmask_b32_e64 v12, v12, 0, s[16:17]
	v_add_f32_e32 v6, v187, v13
	v_cndmask_b32_e64 v13, v13, v6, s[18:19]
	v_cndmask_b32_e64 v13, v13, 0, s[16:17]
	v_cvt_pk_bf16_f32 v12, v12, v13
	global_store_short v72, v12, s[90:91]
	s_add_u32 s90, s90, 0x4000
	s_addc_u32 s91, s91, 0
	global_store_short_d16_hi v72, v12, s[90:91]
	s_add_u32 s90, s90, 0x4000
	s_addc_u32 s91, s91, 0
	v_mfma_f32_32x32x16_bf16 v[32:47], v[108:111], v[156:159], v[32:47]
	v_mul_f32_e32 v10, s48, v71
	v_mul_f32_e32 v11, s49, v71
	v_exp_f32_e32 v10, v10
	v_exp_f32_e32 v11, v11
	s_nop 0
	v_pk_add_f32 v[10:11], v[10:11], v[8:9]
	v_pk_mul_f32 v[10:11], v[10:11], v[26:27]
	v_add_f32_e32 v6, v188, v10
	v_cndmask_b32_e64 v10, v10, v6, s[18:19]
	v_cndmask_b32_e64 v10, v10, 0, s[16:17]
	v_add_f32_e32 v6, v189, v11
	v_cndmask_b32_e64 v11, v11, v6, s[18:19]
	v_cndmask_b32_e64 v11, v11, 0, s[16:17]
	v_cvt_pk_bf16_f32 v10, v10, v11
	global_store_short v72, v10, s[90:91]
	v_mfma_f32_32x32x16_bf16 v[32:47], v[108:111], v[172:175], v[32:47]
	s_add_u32 s90, s90, 0x4000
	s_addc_u32 s91, s91, 0
	global_store_short_d16_hi v72, v10, s[90:91]
	s_add_u32 s90, s90, 0x4000
	s_addc_u32 s91, s91, 0
	v_mul_f32_e32 v12, s52, v71
	v_mul_f32_e32 v13, s53, v71
	v_exp_f32_e32 v12, v12
	v_exp_f32_e32 v13, v13
	s_nop 0
	v_pk_add_f32 v[12:13], v[12:13], v[8:9]
	v_pk_mul_f32 v[12:13], v[12:13], v[28:29]
	v_add_f32_e32 v6, v190, v12
	v_cndmask_b32_e64 v12, v12, v6, s[18:19]
	v_cndmask_b32_e64 v12, v12, 0, s[16:17]
	v_mfma_f32_32x32x16_bf16 v[32:47], v[76:79], v[156:159], v[32:47]
	v_add_f32_e32 v6, v191, v13
	v_cndmask_b32_e64 v13, v13, v6, s[18:19]
	v_cndmask_b32_e64 v13, v13, 0, s[16:17]
	v_cvt_pk_bf16_f32 v12, v12, v13
	global_store_short v72, v12, s[90:91]
	s_add_u32 s90, s90, 0x4000
	s_addc_u32 s91, s91, 0
	global_store_short_d16_hi v72, v12, s[90:91]
	s_waitcnt lgkmcnt(0)
	ds_read_b128 v[144:147], v48 offset:24576
	ds_read_b128 v[148:151], v49 offset:24576
	ds_read_b128 v[152:155], v50 offset:24576
	ds_read_b128 v[156:159], v51 offset:24576
	ds_read_b128 v[160:163], v48 offset:28672
	ds_read_b128 v[164:167], v49 offset:28672
	ds_read_b128 v[168:171], v50 offset:28672
	ds_read_b128 v[172:175], v51 offset:28672
	v_mfma_f32_32x32x16_bf16 v[14:29], v[84:87], v[112:115], 0
	v_add_u32_e32 v70, s55, v3
	v_cvt_f32_i32_e32 v71, v70
	v_mul_f32_e32 v71, 0xb9b8b5c6, v71
	v_sub_u32_e32 v72, 0x1000, v70
	v_add_u32_e32 v73, 0x1000, v70
	v_cndmask_b32_e64 v72, v72, v73, s[14:15]
	v_lshlrev_b32_e32 v72, 1, v72
	s_mov_b64 s[90:91], s[84:85]
	s_add_i32 s55, s55, 32
	s_nop 7
	v_mfma_f32_32x32x16_bf16 v[14:29], v[84:87], v[128:131], v[14:29]
	v_mul_f32_e32 v10, s6, v71
	v_mul_f32_e32 v11, s7, v71
	v_exp_f32_e32 v10, v10
	v_exp_f32_e32 v11, v11
	s_nop 0
	v_pk_add_f32 v[10:11], v[10:11], v[8:9]
	v_pk_mul_f32 v[10:11], v[10:11], v[32:33]
	v_cvt_pk_bf16_f32 v10, v10, v11
	global_store_short v72, v10, s[90:91]
	s_add_u32 s90, s90, 0x4000
	v_mfma_f32_32x32x16_bf16 v[14:29], v[88:91], v[112:115], v[14:29]
	s_addc_u32 s91, s91, 0
	global_store_short_d16_hi v72, v10, s[90:91]
	s_add_u32 s90, s90, 0x4000
	s_addc_u32 s91, s91, 0
	v_mul_f32_e32 v12, s10, v71
	v_mul_f32_e32 v13, s11, v71
	v_exp_f32_e32 v12, v12
	v_exp_f32_e32 v13, v13
	s_nop 0
	v_pk_add_f32 v[12:13], v[12:13], v[8:9]
	v_mfma_f32_32x32x16_bf16 v[14:29], v[92:95], v[116:119], v[14:29]
	v_pk_mul_f32 v[12:13], v[12:13], v[34:35]
	v_cvt_pk_bf16_f32 v12, v12, v13
	global_store_short v72, v12, s[90:91]
	s_add_u32 s90, s90, 0x4000
	s_addc_u32 s91, s91, 0
	global_store_short_d16_hi v72, v12, s[90:91]
	s_add_u32 s90, s90, 0x4000
	s_addc_u32 s91, s91, 0
	v_mul_f32_e32 v10, s24, v71
	v_mul_f32_e32 v11, s62, v71
	v_mfma_f32_32x32x16_bf16 v[14:29], v[92:95], v[132:135], v[14:29]
	v_exp_f32_e32 v10, v10
	v_exp_f32_e32 v11, v11
	s_nop 0
	v_pk_add_f32 v[10:11], v[10:11], v[8:9]
	v_pk_mul_f32 v[10:11], v[10:11], v[36:37]
	v_cvt_pk_bf16_f32 v10, v10, v11
	global_store_short v72, v10, s[90:91]
	s_add_u32 s90, s90, 0x4000
	s_addc_u32 s91, s91, 0
	global_store_short_d16_hi v72, v10, s[90:91]
	v_mfma_f32_32x32x16_bf16 v[14:29], v[96:99], v[116:119], v[14:29]
	s_add_u32 s90, s90, 0x4000
	s_addc_u32 s91, s91, 0
	v_mul_f32_e32 v12, s32, v71
	v_mul_f32_e32 v13, s75, v71
	v_exp_f32_e32 v12, v12
	v_exp_f32_e32 v13, v13
	s_nop 0
	v_pk_add_f32 v[12:13], v[12:13], v[8:9]
	v_pk_mul_f32 v[12:13], v[12:13], v[38:39]
	v_cvt_pk_bf16_f32 v12, v12, v13
	v_mfma_f32_32x32x16_bf16 v[14:29], v[100:103], v[120:123], v[14:29]
	global_store_short v72, v12, s[90:91]
	s_add_u32 s90, s90, 0x4000
	s_addc_u32 s91, s91, 0
	global_store_short_d16_hi v72, v12, s[90:91]
	s_add_u32 s90, s90, 0x4000
	s_addc_u32 s91, s91, 0
	v_mul_f32_e32 v10, s41, v71
	v_mul_f32_e32 v11, s44, v71
	v_exp_f32_e32 v10, v10
	v_exp_f32_e32 v11, v11
	v_mfma_f32_32x32x16_bf16 v[14:29], v[100:103], v[136:139], v[14:29]
	s_nop 0
	v_pk_add_f32 v[10:11], v[10:11], v[8:9]
	v_pk_mul_f32 v[10:11], v[10:11], v[40:41]
	v_cvt_pk_bf16_f32 v10, v10, v11
	global_store_short v72, v10, s[90:91]
	s_add_u32 s90, s90, 0x4000
	s_addc_u32 s91, s91, 0
	global_store_short_d16_hi v72, v10, s[90:91]
	s_add_u32 s90, s90, 0x4000
	s_addc_u32 s91, s91, 0
	v_mfma_f32_32x32x16_bf16 v[14:29], v[104:107], v[120:123], v[14:29]
	v_mul_f32_e32 v12, s45, v71
	v_mul_f32_e32 v13, s47, v71
	v_exp_f32_e32 v12, v12
	v_exp_f32_e32 v13, v13
	s_nop 0
	v_pk_add_f32 v[12:13], v[12:13], v[8:9]
	v_pk_mul_f32 v[12:13], v[12:13], v[42:43]
	v_cvt_pk_bf16_f32 v12, v12, v13
	global_store_short v72, v12, s[90:91]
	s_add_u32 s90, s90, 0x4000
	v_mfma_f32_32x32x16_bf16 v[14:29], v[108:111], v[124:127], v[14:29]
	s_addc_u32 s91, s91, 0
	global_store_short_d16_hi v72, v12, s[90:91]
	s_add_u32 s90, s90, 0x4000
	s_addc_u32 s91, s91, 0
	v_mul_f32_e32 v10, s48, v71
	v_mul_f32_e32 v11, s49, v71
	v_exp_f32_e32 v10, v10
	v_exp_f32_e32 v11, v11
	s_nop 0
	v_pk_add_f32 v[10:11], v[10:11], v[8:9]
	v_mfma_f32_32x32x16_bf16 v[14:29], v[108:111], v[140:143], v[14:29]
	v_pk_mul_f32 v[10:11], v[10:11], v[44:45]
	v_cvt_pk_bf16_f32 v10, v10, v11
	global_store_short v72, v10, s[90:91]
	s_add_u32 s90, s90, 0x4000
	s_addc_u32 s91, s91, 0
	global_store_short_d16_hi v72, v10, s[90:91]
	s_add_u32 s90, s90, 0x4000
	s_addc_u32 s91, s91, 0
	v_mul_f32_e32 v12, s52, v71
	v_mul_f32_e32 v13, s53, v71
	v_mfma_f32_32x32x16_bf16 v[14:29], v[76:79], v[124:127], v[14:29]
	v_exp_f32_e32 v12, v12
	v_exp_f32_e32 v13, v13
	s_nop 0
	v_pk_add_f32 v[12:13], v[12:13], v[8:9]
	v_pk_mul_f32 v[12:13], v[12:13], v[46:47]
	v_cvt_pk_bf16_f32 v12, v12, v13
	global_store_short v72, v12, s[90:91]
	s_add_u32 s90, s90, 0x4000
	s_addc_u32 s91, s91, 0
	global_store_short_d16_hi v72, v12, s[90:91]
	s_waitcnt lgkmcnt(0)
	v_mfma_f32_32x32x16_bf16 v[32:47], v[84:87], v[144:147], 0
	v_add_u32_e32 v70, s55, v3
	v_cvt_f32_i32_e32 v71, v70
	v_mul_f32_e32 v71, 0xb9b8b5c6, v71
	v_sub_u32_e32 v72, 0x1000, v70
	v_add_u32_e32 v73, 0x1000, v70
	v_cndmask_b32_e64 v72, v72, v73, s[14:15]
	v_lshlrev_b32_e32 v72, 1, v72
	s_mov_b64 s[90:91], s[84:85]
	s_add_i32 s55, s55, 32
	s_nop 7
	v_mfma_f32_32x32x16_bf16 v[32:47], v[84:87], v[160:163], v[32:47]
	v_mul_f32_e32 v10, s6, v71
	v_mul_f32_e32 v11, s7, v71
	v_exp_f32_e32 v10, v10
	v_exp_f32_e32 v11, v11
	s_nop 0
	v_pk_add_f32 v[10:11], v[10:11], v[8:9]
	v_pk_mul_f32 v[10:11], v[10:11], v[14:15]
	v_cvt_pk_bf16_f32 v10, v10, v11
	global_store_short v72, v10, s[90:91]
	s_add_u32 s90, s90, 0x4000
	v_mfma_f32_32x32x16_bf16 v[32:47], v[88:91], v[144:147], v[32:47]
	s_addc_u32 s91, s91, 0
	global_store_short_d16_hi v72, v10, s[90:91]
	s_add_u32 s90, s90, 0x4000
	s_addc_u32 s91, s91, 0
	v_mul_f32_e32 v12, s10, v71
	v_mul_f32_e32 v13, s11, v71
	v_exp_f32_e32 v12, v12
	v_exp_f32_e32 v13, v13
	s_nop 0
	v_pk_add_f32 v[12:13], v[12:13], v[8:9]
	v_mfma_f32_32x32x16_bf16 v[32:47], v[92:95], v[148:151], v[32:47]
	v_pk_mul_f32 v[12:13], v[12:13], v[16:17]
	v_cvt_pk_bf16_f32 v12, v12, v13
	global_store_short v72, v12, s[90:91]
	s_add_u32 s90, s90, 0x4000
	s_addc_u32 s91, s91, 0
	global_store_short_d16_hi v72, v12, s[90:91]
	s_add_u32 s90, s90, 0x4000
	s_addc_u32 s91, s91, 0
	v_mul_f32_e32 v10, s24, v71
	v_mul_f32_e32 v11, s62, v71
	v_mfma_f32_32x32x16_bf16 v[32:47], v[92:95], v[164:167], v[32:47]
	v_exp_f32_e32 v10, v10
	v_exp_f32_e32 v11, v11
	s_nop 0
	v_pk_add_f32 v[10:11], v[10:11], v[8:9]
	v_pk_mul_f32 v[10:11], v[10:11], v[18:19]
	v_cvt_pk_bf16_f32 v10, v10, v11
	global_store_short v72, v10, s[90:91]
	s_add_u32 s90, s90, 0x4000
	s_addc_u32 s91, s91, 0
	global_store_short_d16_hi v72, v10, s[90:91]
	v_mfma_f32_32x32x16_bf16 v[32:47], v[96:99], v[148:151], v[32:47]
	s_add_u32 s90, s90, 0x4000
	s_addc_u32 s91, s91, 0
	v_mul_f32_e32 v12, s32, v71
	v_mul_f32_e32 v13, s75, v71
	v_exp_f32_e32 v12, v12
	v_exp_f32_e32 v13, v13
	s_nop 0
	v_pk_add_f32 v[12:13], v[12:13], v[8:9]
	v_pk_mul_f32 v[12:13], v[12:13], v[20:21]
	v_cvt_pk_bf16_f32 v12, v12, v13
	v_mfma_f32_32x32x16_bf16 v[32:47], v[100:103], v[152:155], v[32:47]
	global_store_short v72, v12, s[90:91]
	s_add_u32 s90, s90, 0x4000
	s_addc_u32 s91, s91, 0
	global_store_short_d16_hi v72, v12, s[90:91]
	s_add_u32 s90, s90, 0x4000
	s_addc_u32 s91, s91, 0
	v_mul_f32_e32 v10, s41, v71
	v_mul_f32_e32 v11, s44, v71
	v_exp_f32_e32 v10, v10
	v_exp_f32_e32 v11, v11
	v_mfma_f32_32x32x16_bf16 v[32:47], v[100:103], v[168:171], v[32:47]
	s_nop 0
	v_pk_add_f32 v[10:11], v[10:11], v[8:9]
	v_pk_mul_f32 v[10:11], v[10:11], v[22:23]
	v_cvt_pk_bf16_f32 v10, v10, v11
	global_store_short v72, v10, s[90:91]
	s_add_u32 s90, s90, 0x4000
	s_addc_u32 s91, s91, 0
	global_store_short_d16_hi v72, v10, s[90:91]
	s_add_u32 s90, s90, 0x4000
	s_addc_u32 s91, s91, 0
	v_mfma_f32_32x32x16_bf16 v[32:47], v[104:107], v[152:155], v[32:47]
	v_mul_f32_e32 v12, s45, v71
	v_mul_f32_e32 v13, s47, v71
	v_exp_f32_e32 v12, v12
	v_exp_f32_e32 v13, v13
	s_nop 0
	v_pk_add_f32 v[12:13], v[12:13], v[8:9]
	v_pk_mul_f32 v[12:13], v[12:13], v[24:25]
	v_cvt_pk_bf16_f32 v12, v12, v13
	global_store_short v72, v12, s[90:91]
	s_add_u32 s90, s90, 0x4000
	v_mfma_f32_32x32x16_bf16 v[32:47], v[108:111], v[156:159], v[32:47]
	s_addc_u32 s91, s91, 0
	global_store_short_d16_hi v72, v12, s[90:91]
	s_add_u32 s90, s90, 0x4000
	s_addc_u32 s91, s91, 0
	v_mul_f32_e32 v10, s48, v71
	v_mul_f32_e32 v11, s49, v71
	v_exp_f32_e32 v10, v10
	v_exp_f32_e32 v11, v11
	s_nop 0
	v_pk_add_f32 v[10:11], v[10:11], v[8:9]
	v_mfma_f32_32x32x16_bf16 v[32:47], v[108:111], v[172:175], v[32:47]
	v_pk_mul_f32 v[10:11], v[10:11], v[26:27]
	v_cvt_pk_bf16_f32 v10, v10, v11
	global_store_short v72, v10, s[90:91]
	s_add_u32 s90, s90, 0x4000
	s_addc_u32 s91, s91, 0
	global_store_short_d16_hi v72, v10, s[90:91]
	s_add_u32 s90, s90, 0x4000
	s_addc_u32 s91, s91, 0
	v_mul_f32_e32 v12, s52, v71
	v_mul_f32_e32 v13, s53, v71
	v_mfma_f32_32x32x16_bf16 v[32:47], v[76:79], v[156:159], v[32:47]
	v_exp_f32_e32 v12, v12
	v_exp_f32_e32 v13, v13
	s_nop 0
	v_pk_add_f32 v[12:13], v[12:13], v[8:9]
	v_pk_mul_f32 v[12:13], v[12:13], v[28:29]
	v_cvt_pk_bf16_f32 v12, v12, v13
	global_store_short v72, v12, s[90:91]
	s_add_u32 s90, s90, 0x4000
	s_addc_u32 s91, s91, 0
	global_store_short_d16_hi v72, v12, s[90:91]
	s_nop 7
	v_add_u32_e32 v70, s55, v3
	v_cvt_f32_i32_e32 v71, v70
	v_mul_f32_e32 v71, 0xb9b8b5c6, v71
	v_sub_u32_e32 v72, 0x1000, v70
	v_add_u32_e32 v73, 0x1000, v70
	v_cndmask_b32_e64 v72, v72, v73, s[14:15]
	v_lshlrev_b32_e32 v72, 1, v72
	s_mov_b64 s[90:91], s[84:85]
	s_nop 7
	v_mul_f32_e32 v10, s6, v71
	v_mul_f32_e32 v11, s7, v71
	v_exp_f32_e32 v10, v10
	v_exp_f32_e32 v11, v11
	s_nop 0
	v_pk_add_f32 v[10:11], v[10:11], v[8:9]
	v_pk_mul_f32 v[10:11], v[10:11], v[32:33]
	v_cvt_pk_bf16_f32 v10, v10, v11
	global_store_short v72, v10, s[90:91]
	s_add_u32 s90, s90, 0x4000
	s_addc_u32 s91, s91, 0
	global_store_short_d16_hi v72, v10, s[90:91]
	s_add_u32 s90, s90, 0x4000
	s_addc_u32 s91, s91, 0
	v_mul_f32_e32 v12, s10, v71
	v_mul_f32_e32 v13, s11, v71
	v_exp_f32_e32 v12, v12
	v_exp_f32_e32 v13, v13
	s_nop 0
	v_pk_add_f32 v[12:13], v[12:13], v[8:9]
	v_pk_mul_f32 v[12:13], v[12:13], v[34:35]
	v_cvt_pk_bf16_f32 v12, v12, v13
	global_store_short v72, v12, s[90:91]
	s_add_u32 s90, s90, 0x4000
	s_addc_u32 s91, s91, 0
	global_store_short_d16_hi v72, v12, s[90:91]
	s_add_u32 s90, s90, 0x4000
	s_addc_u32 s91, s91, 0
	v_mul_f32_e32 v10, s24, v71
	v_mul_f32_e32 v11, s62, v71
	v_exp_f32_e32 v10, v10
	v_exp_f32_e32 v11, v11
	s_nop 0
	v_pk_add_f32 v[10:11], v[10:11], v[8:9]
	v_pk_mul_f32 v[10:11], v[10:11], v[36:37]
	v_cvt_pk_bf16_f32 v10, v10, v11
	global_store_short v72, v10, s[90:91]
	s_add_u32 s90, s90, 0x4000
	s_addc_u32 s91, s91, 0
	global_store_short_d16_hi v72, v10, s[90:91]
	s_add_u32 s90, s90, 0x4000
	s_addc_u32 s91, s91, 0
	v_mul_f32_e32 v12, s32, v71
	v_mul_f32_e32 v13, s75, v71
	v_exp_f32_e32 v12, v12
	v_exp_f32_e32 v13, v13
	s_nop 0
	v_pk_add_f32 v[12:13], v[12:13], v[8:9]
	v_pk_mul_f32 v[12:13], v[12:13], v[38:39]
	v_cvt_pk_bf16_f32 v12, v12, v13
	global_store_short v72, v12, s[90:91]
	s_add_u32 s90, s90, 0x4000
	s_addc_u32 s91, s91, 0
	global_store_short_d16_hi v72, v12, s[90:91]
	s_add_u32 s90, s90, 0x4000
	s_addc_u32 s91, s91, 0
	v_mul_f32_e32 v10, s41, v71
	v_mul_f32_e32 v11, s44, v71
	v_exp_f32_e32 v10, v10
	v_exp_f32_e32 v11, v11
	s_nop 0
	v_pk_add_f32 v[10:11], v[10:11], v[8:9]
	v_pk_mul_f32 v[10:11], v[10:11], v[40:41]
	v_cvt_pk_bf16_f32 v10, v10, v11
	global_store_short v72, v10, s[90:91]
	s_add_u32 s90, s90, 0x4000
	s_addc_u32 s91, s91, 0
	global_store_short_d16_hi v72, v10, s[90:91]
	s_add_u32 s90, s90, 0x4000
	s_addc_u32 s91, s91, 0
	v_mul_f32_e32 v12, s45, v71
	v_mul_f32_e32 v13, s47, v71
	v_exp_f32_e32 v12, v12
	v_exp_f32_e32 v13, v13
	s_nop 0
	v_pk_add_f32 v[12:13], v[12:13], v[8:9]
	v_pk_mul_f32 v[12:13], v[12:13], v[42:43]
	v_cvt_pk_bf16_f32 v12, v12, v13
	global_store_short v72, v12, s[90:91]
	s_add_u32 s90, s90, 0x4000
	s_addc_u32 s91, s91, 0
	global_store_short_d16_hi v72, v12, s[90:91]
	s_add_u32 s90, s90, 0x4000
	s_addc_u32 s91, s91, 0
	v_mul_f32_e32 v10, s48, v71
	v_mul_f32_e32 v11, s49, v71
	v_exp_f32_e32 v10, v10
	v_exp_f32_e32 v11, v11
	s_nop 0
	v_pk_add_f32 v[10:11], v[10:11], v[8:9]
	v_pk_mul_f32 v[10:11], v[10:11], v[44:45]
	v_cvt_pk_bf16_f32 v10, v10, v11
	global_store_short v72, v10, s[90:91]
	s_add_u32 s90, s90, 0x4000
	s_addc_u32 s91, s91, 0
	global_store_short_d16_hi v72, v10, s[90:91]
	s_add_u32 s90, s90, 0x4000
	s_addc_u32 s91, s91, 0
	v_mul_f32_e32 v12, s52, v71
	v_mul_f32_e32 v13, s53, v71
	v_exp_f32_e32 v12, v12
	v_exp_f32_e32 v13, v13
	s_nop 0
	v_pk_add_f32 v[12:13], v[12:13], v[8:9]
	v_pk_mul_f32 v[12:13], v[12:13], v[46:47]
	v_cvt_pk_bf16_f32 v12, v12, v13
	global_store_short v72, v12, s[90:91]
	s_add_u32 s90, s90, 0x4000
	s_addc_u32 s91, s91, 0
	global_store_short_d16_hi v72, v12, s[90:91]
	s_barrier
	s_add_i32 s93, s93, s70
	s_branch .Lpf_item
.Lpf_end:
	s_cmpk_lg_u32 s70, 0x100
	s_cbranch_scc1 .Lpf_done
	s_bitcmp1_b32 s2, 3
	s_cbranch_scc1 .Lp2_tiles
